# in-proj K loop: B fragment LDS reads of phases 1/5 issued inside the preceding MFMA section, DMA wait moved one barrier earlier
# baseline (speedup 1.0000x reference)
; #define PG8_STAGE(bufoff, gbase, voff) do { _Pragma("unroll") for (int _i = 0; _i < 2; ++_i) \
;         __builtin_amdgcn_global_load_lds((const unsigned*)((const char*)(gbase) + (voff)[_i]), (LAS unsigned*)(lds + (bufoff) + ldsw + _i * 8192), 16, 0, 0); } while (0)
; #define PG8_LDA(dst, b, h) do { _Pragma("unroll") for (int m = 0; m < 4; ++m) _Pragma("unroll") for (int k = 0; k < 2; ++k) dst[m][k] = *(const LAS h8*)(lds + PG8_SA(b, h) + aoff + m * 2048 + k * 1024); } while (0)
; #define PG8_LDB(dst, b, h) do { _Pragma("unroll") for (int n = 0; n < 2; ++n) _Pragma("unroll") for (int k = 0; k < 2; ++k) dst[n][k] = *(const LAS h8*)(lds + PG8_SB(b, h) + boff + n * 2048 + k * 1024); } while (0)
; #define PG8_WAIT_L(n) asm volatile("s_waitcnt lgkmcnt(" #n ")" ::: "memory")
; #define PG8_BAR __builtin_amdgcn_s_barrier()
; #define PG8_SCHED __builtin_amdgcn_sched_barrier(0)
; template <class Epi>
; __device__ __forceinline__ void gemm_phase(LAS unsigned char* lds, const Gemm g, const StaticOrder& S, const Epi& E, const int tid) {
;     ...
;         const char* nA = has_next ? (const char*)g.A + (size_t)nxt.pm * tstep : cA; const char* nB = has_next ? (const char*)g.Bt + (size_t)nxt.pn * tstep : cB;
;         for (int t = 0; t < nt; t += 2) {
;             const bool last = (t == nt - 2);
;             const char* a1 = cA + (size_t)(t + 1) * kstep;
;             const char* a2 = last ? nA : cA + (size_t)(t + 2) * kstep; const char* b2 = last ? nB : cB + (size_t)(t + 2) * kstep;
;             const char* a3 = a2 + kstep; const char* b3 = b2 + kstep;
;             if constexpr (Epi::HAS_MID) { if (t == (nt >> 1)) E.mid(acc, cur, wr, wc, fr, fq); }
;             PG8_LDB(B0, 0, 0); PG8_SCHED; PG8_LDA(At, 0, 0); PG8_STAGE(PG8_SA(1, 1), a1 + hstep, voffA);
;             PG8_WAIT_L(8); PG8_BAR; PG8_WAIT_L(0); PG8_MMA(0, 0, At, B0); PG8_BAR; PG8_SCHED;
;     ...
; #pragma unroll
;         for (int a = 0; a < 2; ++a)
; #pragma unroll
;             for (int b = 0; b < 2; ++b)
; #pragma unroll
;                 for (int m = 0; m < 4; ++m)
; #pragma unroll
;                     for (int n = 0; n < 2; ++n) acc[a][b][m][n] = (f32x4){0.f, 0.f, 0.f, 0.f};
;         cur = nxt; cA = nA; cB = nB; ++ui;
.LBB0_331:
	s_ashr_i32 s9, s8, 31
	v_cmp_lt_i64_e32 vcc, s[10:11], v[154:155]
	s_lshl_b64 s[10:11], s[8:9], 20
	s_add_u32 s10, s96, s10
	s_addc_u32 s11, s74, s11
	s_and_b64 s[12:13], vcc, exec
	s_cselect_b32 s9, s11, s15
	s_cselect_b32 s50, s10, s14
	s_ashr_i32 s1, s0, 31
	s_lshl_b64 s[12:13], s[0:1], 20
	s_add_u32 s12, s24, s12
	s_addc_u32 s13, s25, s13
	s_and_b64 s[22:23], vcc, exec
	s_cselect_b32 s1, s13, s19
	s_cselect_b32 s51, s12, s18
	s_add_u32 s14, s14, 0x80080
	s_addc_u32 s15, s15, 0
	s_add_u32 s52, s18, 0x100
	v_mov_b32_e32 v4, 0
	s_addc_u32 s53, s19, 0
	s_mov_b32 s54, -2
	v_mov_b32_e32 v5, v4
	v_mov_b32_e32 v6, v4
	v_mov_b32_e32 v7, v4
	v_mov_b32_e32 v8, v4
	v_mov_b32_e32 v9, v4
	v_mov_b32_e32 v10, v4
	v_mov_b32_e32 v11, v4
	v_mov_b32_e32 v24, v4
	v_mov_b32_e32 v25, v4
	v_mov_b32_e32 v26, v4
	v_mov_b32_e32 v27, v4
	v_mov_b32_e32 v20, v4
	v_mov_b32_e32 v21, v4
	v_mov_b32_e32 v22, v4
	v_mov_b32_e32 v23, v4
	v_mov_b32_e32 v40, v4
	v_mov_b32_e32 v41, v4
	v_mov_b32_e32 v42, v4
	v_mov_b32_e32 v43, v4
	v_mov_b32_e32 v36, v4
	v_mov_b32_e32 v37, v4
	v_mov_b32_e32 v38, v4
	v_mov_b32_e32 v39, v4
	v_mov_b32_e32 v56, v4
	v_mov_b32_e32 v57, v4
	v_mov_b32_e32 v58, v4
	v_mov_b32_e32 v59, v4
	v_mov_b32_e32 v52, v4
	v_mov_b32_e32 v53, v4
	v_mov_b32_e32 v54, v4
	v_mov_b32_e32 v55, v4
	v_mov_b32_e32 v16, v4
	v_mov_b32_e32 v17, v4
	v_mov_b32_e32 v18, v4
	v_mov_b32_e32 v19, v4
	v_mov_b32_e32 v12, v4
	v_mov_b32_e32 v13, v4
	v_mov_b32_e32 v14, v4
	v_mov_b32_e32 v15, v4
	v_mov_b32_e32 v32, v4
	v_mov_b32_e32 v33, v4
	v_mov_b32_e32 v34, v4
	v_mov_b32_e32 v35, v4
	v_mov_b32_e32 v28, v4
	v_mov_b32_e32 v29, v4
	v_mov_b32_e32 v30, v4
	v_mov_b32_e32 v31, v4
	v_mov_b32_e32 v48, v4
	v_mov_b32_e32 v49, v4
	v_mov_b32_e32 v50, v4
	v_mov_b32_e32 v51, v4
	v_mov_b32_e32 v44, v4
	v_mov_b32_e32 v45, v4
	v_mov_b32_e32 v46, v4
	v_mov_b32_e32 v47, v4
	v_mov_b32_e32 v64, v4
	v_mov_b32_e32 v65, v4
	v_mov_b32_e32 v66, v4
	v_mov_b32_e32 v67, v4
	v_mov_b32_e32 v60, v4
	v_mov_b32_e32 v61, v4
	v_mov_b32_e32 v62, v4
	v_mov_b32_e32 v63, v4
	v_mov_b32_e32 v72, v4
	v_mov_b32_e32 v73, v4
	v_mov_b32_e32 v74, v4
	v_mov_b32_e32 v75, v4
	v_mov_b32_e32 v68, v4
	v_mov_b32_e32 v69, v4
	v_mov_b32_e32 v70, v4
	v_mov_b32_e32 v71, v4
	v_mov_b32_e32 v88, v4
	v_mov_b32_e32 v89, v4
	v_mov_b32_e32 v90, v4
	v_mov_b32_e32 v91, v4
	v_mov_b32_e32 v84, v4
	v_mov_b32_e32 v85, v4
	v_mov_b32_e32 v86, v4
	v_mov_b32_e32 v87, v4
	v_mov_b32_e32 v104, v4
	v_mov_b32_e32 v105, v4
	v_mov_b32_e32 v106, v4
	v_mov_b32_e32 v107, v4
	v_mov_b32_e32 v100, v4
	v_mov_b32_e32 v101, v4
	v_mov_b32_e32 v102, v4
	v_mov_b32_e32 v103, v4
	v_mov_b32_e32 v120, v4
	v_mov_b32_e32 v121, v4
	v_mov_b32_e32 v122, v4
	v_mov_b32_e32 v123, v4
	v_mov_b32_e32 v116, v4
	v_mov_b32_e32 v117, v4
	v_mov_b32_e32 v118, v4
	v_mov_b32_e32 v119, v4
	v_mov_b32_e32 v80, v4
	v_mov_b32_e32 v81, v4
	v_mov_b32_e32 v82, v4
	v_mov_b32_e32 v83, v4
	v_mov_b32_e32 v76, v4
	v_mov_b32_e32 v77, v4
	v_mov_b32_e32 v78, v4
	v_mov_b32_e32 v79, v4
	v_mov_b32_e32 v96, v4
	v_mov_b32_e32 v97, v4
	v_mov_b32_e32 v98, v4
	v_mov_b32_e32 v99, v4
	v_mov_b32_e32 v92, v4
	v_mov_b32_e32 v93, v4
	v_mov_b32_e32 v94, v4
	v_mov_b32_e32 v95, v4
	v_mov_b32_e32 v112, v4
	v_mov_b32_e32 v113, v4
	v_mov_b32_e32 v114, v4
	v_mov_b32_e32 v115, v4
	v_mov_b32_e32 v108, v4
	v_mov_b32_e32 v109, v4
	v_mov_b32_e32 v110, v4
	v_mov_b32_e32 v111, v4
	v_mov_b32_e32 v128, v4
	v_mov_b32_e32 v129, v4
	v_mov_b32_e32 v130, v4
	v_mov_b32_e32 v131, v4
	v_mov_b32_e32 v124, v4
	v_mov_b32_e32 v125, v4
	v_mov_b32_e32 v126, v4
	v_mov_b32_e32 v127, v4
	v_add_u32_e32 v157, 0x10000, v140
	ds_read_b128 v[144:147], v157
	ds_read_b128 v[162:165], v157 offset:1024
	ds_read_b128 v[166:169], v157 offset:2048
	ds_read_b128 v[170:173], v157 offset:3072
.LBB0_332:
	s_add_u32 s18, s14, 0xfff80080
	s_addc_u32 s19, s15, -1
	s_add_i32 s55, 0, 0x10000
	s_cmp_eq_u32 s54, 28
	s_cselect_b32 s23, s9, s19
	s_cselect_b32 s22, s50, s18
	s_cselect_b32 s19, s1, s53
	s_cselect_b32 s18, s51, s52
	s_add_i32 m0, s39, 0xc000
	ds_read_b128 v[174:177], v143
	ds_read_b128 v[190:193], v143 offset:1024
	ds_read_b128 v[194:197], v143 offset:2048
	ds_read_b128 v[198:201], v143 offset:3072
	ds_read_b128 v[202:205], v143 offset:4096
	ds_read_b128 v[206:209], v143 offset:5120
	ds_read_b128 v[210:213], v143 offset:6144
	ds_read_b128 v[214:217], v143 offset:7168
	global_load_lds_dwordx4 v136, s[14:15]
	s_add_i32 m0, s39, 0xe000
	s_nop 0
	global_load_lds_dwordx4 v138, s[14:15]
	s_waitcnt lgkmcnt(8)
	s_barrier
	s_waitcnt lgkmcnt(0)
	s_waitcnt lgkmcnt(0)
	v_mfma_f32_16x16x32_bf16 v[124:127], v[144:147], v[174:177], v[124:127]
	v_mfma_f32_16x16x32_bf16 v[128:131], v[166:169], v[174:177], v[128:131]
	v_mfma_f32_16x16x32_bf16 v[108:111], v[144:147], v[194:197], v[108:111]
	v_mfma_f32_16x16x32_bf16 v[112:115], v[166:169], v[194:197], v[112:115]
	v_mfma_f32_16x16x32_bf16 v[92:95], v[144:147], v[202:205], v[92:95]
	v_mfma_f32_16x16x32_bf16 v[96:99], v[166:169], v[202:205], v[96:99]
	v_mfma_f32_16x16x32_bf16 v[76:79], v[144:147], v[210:213], v[76:79]
	v_mfma_f32_16x16x32_bf16 v[80:83], v[166:169], v[210:213], v[80:83]
	v_mfma_f32_16x16x32_bf16 v[124:127], v[162:165], v[190:193], v[124:127]
	v_mfma_f32_16x16x32_bf16 v[128:131], v[170:173], v[190:193], v[128:131]
	v_mfma_f32_16x16x32_bf16 v[108:111], v[162:165], v[198:201], v[108:111]
	v_mfma_f32_16x16x32_bf16 v[112:115], v[170:173], v[198:201], v[112:115]
	v_mfma_f32_16x16x32_bf16 v[92:95], v[162:165], v[206:209], v[92:95]
	v_mfma_f32_16x16x32_bf16 v[96:99], v[170:173], v[206:209], v[96:99]
	v_mfma_f32_16x16x32_bf16 v[76:79], v[162:165], v[214:217], v[76:79]
	v_mfma_f32_16x16x32_bf16 v[80:83], v[170:173], v[214:217], v[80:83]
	s_barrier
; #define PG8_STAGE(bufoff, gbase, voff) do { _Pragma("unroll") for (int _i = 0; _i < 2; ++_i) \
;         __builtin_amdgcn_global_load_lds((const unsigned*)((const char*)(gbase) + (voff)[_i]), (LAS unsigned*)(lds + (bufoff) + ldsw + _i * 8192), 16, 0, 0); } while (0)
; #define PG8_LDA(dst, b, h) do { _Pragma("unroll") for (int m = 0; m < 4; ++m) _Pragma("unroll") for (int k = 0; k < 2; ++k) dst[m][k] = *(const LAS h8*)(lds + PG8_SA(b, h) + aoff + m * 2048 + k * 1024); } while (0)
; #define PG8_LDB(dst, b, h) do { _Pragma("unroll") for (int n = 0; n < 2; ++n) _Pragma("unroll") for (int k = 0; k < 2; ++k) dst[n][k] = *(const LAS h8*)(lds + PG8_SB(b, h) + boff + n * 2048 + k * 1024); } while (0)
; #define PG8_WAIT_V(n) asm volatile("s_waitcnt vmcnt(" #n ")" ::: "memory")
; #define PG8_WAIT_L(n) asm volatile("s_waitcnt lgkmcnt(" #n ")" ::: "memory")
; #define PG8_BAR __builtin_amdgcn_s_barrier()
; #define PG8_SCHED __builtin_amdgcn_sched_barrier(0)
; template <class Epi>
; __device__ __forceinline__ void gemm_phase(LAS unsigned char* lds, const Gemm g, const StaticOrder& S, const Epi& E, const int tid) {
;     ...
;             PG8_LDB(B1, 0, 1); PG8_STAGE(PG8_SB(0, 0), b2, voffB);
;             PG8_BAR; PG8_WAIT_L(0); PG8_MMA(0, 1, At, B1); PG8_BAR;
;             PG8_LDA(At, 0, 1); PG8_STAGE(PG8_SA(0, 0), a2, voffA);
;             PG8_BAR; PG8_WAIT_L(0); PG8_MMA(1, 0, At, B0); PG8_BAR; PG8_SCHED;
;             PG8_STAGE(PG8_SB(0, 1), b2 + hstepB, voffB);
;             PG8_WAIT_V(6); PG8_BAR; PG8_MMA(1, 1, At, B1); PG8_BAR;
;             PG8_LDB(B0, 1, 0); PG8_SCHED; PG8_LDA(At, 1, 0); PG8_STAGE(PG8_SA(0, 1), a2 + hstep, voffA);
;             PG8_WAIT_L(8); PG8_BAR; PG8_WAIT_L(0); PG8_MMA(0, 0, At, B0); PG8_BAR; PG8_SCHED;
	s_add_i32 s58, 0, 0x14000
	s_add_i32 s55, s55, s38
	v_add_u32_e32 v157, s58, v140
	v_lshl_add_u64 v[178:179], s[18:19], 0, v[2:3]
	s_mov_b32 m0, s55
	ds_read_b128 v[218:221], v157
	ds_read_b128 v[222:225], v157 offset:1024
	ds_read_b128 v[226:229], v157 offset:2048
	ds_read_b128 v[230:233], v157 offset:3072
	global_load_lds_dwordx4 v[178:179], off
	v_lshl_add_u64 v[234:235], s[18:19], 0, v[0:1]
	s_add_i32 m0, s55, 0x2000
	s_nop 0
	global_load_lds_dwordx4 v[234:235], off
	s_barrier
	s_waitcnt lgkmcnt(0)
	s_waitcnt lgkmcnt(0)
	v_mfma_f32_16x16x32_bf16 v[116:119], v[218:221], v[174:177], v[116:119]
	v_mfma_f32_16x16x32_bf16 v[120:123], v[226:229], v[174:177], v[120:123]
	v_mfma_f32_16x16x32_bf16 v[100:103], v[218:221], v[194:197], v[100:103]
	v_mfma_f32_16x16x32_bf16 v[104:107], v[226:229], v[194:197], v[104:107]
	v_mfma_f32_16x16x32_bf16 v[84:87], v[218:221], v[202:205], v[84:87]
	v_mfma_f32_16x16x32_bf16 v[88:91], v[226:229], v[202:205], v[88:91]
	v_mfma_f32_16x16x32_bf16 v[68:71], v[218:221], v[210:213], v[68:71]
	v_mfma_f32_16x16x32_bf16 v[72:75], v[226:229], v[210:213], v[72:75]
	v_mfma_f32_16x16x32_bf16 v[116:119], v[222:225], v[190:193], v[116:119]
	v_mfma_f32_16x16x32_bf16 v[120:123], v[230:233], v[190:193], v[120:123]
	v_mfma_f32_16x16x32_bf16 v[100:103], v[222:225], v[198:201], v[100:103]
	v_mfma_f32_16x16x32_bf16 v[104:107], v[230:233], v[198:201], v[104:107]
	v_mfma_f32_16x16x32_bf16 v[84:87], v[222:225], v[206:209], v[84:87]
	v_mfma_f32_16x16x32_bf16 v[88:91], v[230:233], v[206:209], v[88:91]
	v_mfma_f32_16x16x32_bf16 v[68:71], v[222:225], v[214:217], v[68:71]
	v_mfma_f32_16x16x32_bf16 v[72:75], v[230:233], v[214:217], v[72:75]
	s_mov_b32 m0, s39
	v_lshl_add_u64 v[236:237], s[22:23], 0, v[134:135]
	s_barrier
	ds_read_b128 v[174:177], v143 offset:16384
	ds_read_b128 v[190:193], v143 offset:17408
	ds_read_b128 v[194:197], v143 offset:18432
	ds_read_b128 v[198:201], v143 offset:19456
	ds_read_b128 v[202:205], v143 offset:20480
	ds_read_b128 v[206:209], v143 offset:21504
	ds_read_b128 v[210:213], v143 offset:22528
	ds_read_b128 v[214:217], v143 offset:23552
	global_load_lds_dwordx4 v[236:237], off
	v_lshl_add_u64 v[238:239], s[22:23], 0, v[132:133]
	s_mov_b32 m0, s40
	s_nop 0
	global_load_lds_dwordx4 v[238:239], off
	s_barrier
	s_waitcnt lgkmcnt(0)
	s_waitcnt lgkmcnt(0)
	v_mfma_f32_16x16x32_bf16 v[60:63], v[144:147], v[174:177], v[60:63]
	v_mfma_f32_16x16x32_bf16 v[64:67], v[166:169], v[174:177], v[64:67]
	v_mfma_f32_16x16x32_bf16 v[44:47], v[144:147], v[194:197], v[44:47]
	v_mfma_f32_16x16x32_bf16 v[48:51], v[166:169], v[194:197], v[48:51]
	v_mfma_f32_16x16x32_bf16 v[28:31], v[144:147], v[202:205], v[28:31]
	v_mfma_f32_16x16x32_bf16 v[32:35], v[166:169], v[202:205], v[32:35]
	v_mfma_f32_16x16x32_bf16 v[12:15], v[144:147], v[210:213], v[12:15]
	v_mfma_f32_16x16x32_bf16 v[16:19], v[166:169], v[210:213], v[16:19]
	v_mfma_f32_16x16x32_bf16 v[60:63], v[162:165], v[190:193], v[60:63]
	v_mfma_f32_16x16x32_bf16 v[64:67], v[170:173], v[190:193], v[64:67]
	v_mfma_f32_16x16x32_bf16 v[44:47], v[162:165], v[198:201], v[44:47]
	v_mfma_f32_16x16x32_bf16 v[48:51], v[170:173], v[198:201], v[48:51]
	v_mfma_f32_16x16x32_bf16 v[28:31], v[162:165], v[206:209], v[28:31]
	v_mfma_f32_16x16x32_bf16 v[32:35], v[170:173], v[206:209], v[32:35]
	v_mfma_f32_16x16x32_bf16 v[12:15], v[162:165], v[214:217], v[12:15]
	v_mfma_f32_16x16x32_bf16 v[16:19], v[170:173], v[214:217], v[16:19]
	s_waitcnt vmcnt(4)
	s_barrier
	s_add_u32 s56, s18, 0x20000
	s_addc_u32 s57, s19, 0
	s_add_i32 s55, s58, s38
	s_mov_b32 m0, s55
	s_nop 0
	global_load_lds_dwordx4 v2, s[56:57]
	s_add_i32 m0, s55, 0x2000
	s_nop 0
	global_load_lds_dwordx4 v0, s[56:57]
	s_waitcnt vmcnt(6)
	s_barrier
	v_add_u32_e32 v157, 0x18000, v140
	ds_read_b128 v[144:147], v157
	ds_read_b128 v[162:165], v157 offset:1024
	ds_read_b128 v[166:169], v157 offset:2048
	ds_read_b128 v[170:173], v157 offset:3072
	v_mfma_f32_16x16x32_bf16 v[52:55], v[218:221], v[174:177], v[52:55]
	v_mfma_f32_16x16x32_bf16 v[56:59], v[226:229], v[174:177], v[56:59]
	v_mfma_f32_16x16x32_bf16 v[36:39], v[218:221], v[194:197], v[36:39]
	v_mfma_f32_16x16x32_bf16 v[40:43], v[226:229], v[194:197], v[40:43]
	v_mfma_f32_16x16x32_bf16 v[20:23], v[218:221], v[202:205], v[20:23]
	v_mfma_f32_16x16x32_bf16 v[24:27], v[226:229], v[202:205], v[24:27]
	v_mfma_f32_16x16x32_bf16 v[8:11], v[218:221], v[210:213], v[8:11]
	v_mfma_f32_16x16x32_bf16 v[4:7], v[226:229], v[210:213], v[4:7]
	v_mfma_f32_16x16x32_bf16 v[52:55], v[222:225], v[190:193], v[52:55]
	v_mfma_f32_16x16x32_bf16 v[56:59], v[230:233], v[190:193], v[56:59]
	v_mfma_f32_16x16x32_bf16 v[36:39], v[222:225], v[198:201], v[36:39]
	v_mfma_f32_16x16x32_bf16 v[40:43], v[230:233], v[198:201], v[40:43]
	v_mfma_f32_16x16x32_bf16 v[20:23], v[222:225], v[206:209], v[20:23]
	v_mfma_f32_16x16x32_bf16 v[24:27], v[230:233], v[206:209], v[24:27]
	v_mfma_f32_16x16x32_bf16 v[8:11], v[222:225], v[214:217], v[8:11]
	v_mfma_f32_16x16x32_bf16 v[4:7], v[230:233], v[214:217], v[4:7]
	s_add_i32 s55, 0, 0x18000
	s_barrier
	s_add_u32 s22, s22, 0x80000
	s_addc_u32 s23, s23, 0
	s_mov_b32 m0, s41
	ds_read_b128 v[174:177], v143 offset:32768
	ds_read_b128 v[190:193], v143 offset:33792
	ds_read_b128 v[194:197], v143 offset:34816
	ds_read_b128 v[198:201], v143 offset:35840
	ds_read_b128 v[202:205], v143 offset:36864
	ds_read_b128 v[206:209], v143 offset:37888
	ds_read_b128 v[210:213], v143 offset:38912
	ds_read_b128 v[214:217], v143 offset:39936
	global_load_lds_dwordx4 v134, s[22:23]
	s_mov_b32 m0, s42
	s_nop 0
	global_load_lds_dwordx4 v132, s[22:23]
	s_waitcnt lgkmcnt(8)
	s_barrier
; #define PG8_STAGE(bufoff, gbase, voff) do { _Pragma("unroll") for (int _i = 0; _i < 2; ++_i) \
;         __builtin_amdgcn_global_load_lds((const unsigned*)((const char*)(gbase) + (voff)[_i]), (LAS unsigned*)(lds + (bufoff) + ldsw + _i * 8192), 16, 0, 0); } while (0)
; #define PG8_LDA(dst, b, h) do { _Pragma("unroll") for (int m = 0; m < 4; ++m) _Pragma("unroll") for (int k = 0; k < 2; ++k) dst[m][k] = *(const LAS h8*)(lds + PG8_SA(b, h) + aoff + m * 2048 + k * 1024); } while (0)
; #define PG8_LDB(dst, b, h) do { _Pragma("unroll") for (int n = 0; n < 2; ++n) _Pragma("unroll") for (int k = 0; k < 2; ++k) dst[n][k] = *(const LAS h8*)(lds + PG8_SB(b, h) + boff + n * 2048 + k * 1024); } while (0)
; #define PG8_WAIT_V(n) asm volatile("s_waitcnt vmcnt(" #n ")" ::: "memory")
; #define PG8_WAIT_L(n) asm volatile("s_waitcnt lgkmcnt(" #n ")" ::: "memory")
; #define PG8_BAR __builtin_amdgcn_s_barrier()
; #define PG8_SCHED __builtin_amdgcn_sched_barrier(0)
; template <class Epi>
; __device__ __forceinline__ void gemm_phase(LAS unsigned char* lds, const Gemm g, const StaticOrder& S, const Epi& E, const int tid) {
;     ...
;             PG8_WAIT_L(8); PG8_BAR; PG8_WAIT_L(0); PG8_MMA(0, 0, At, B0); PG8_BAR; PG8_SCHED;
;             PG8_LDB(B1, 1, 1); PG8_STAGE(PG8_SB(1, 0), b3, voffB);
;             PG8_BAR; PG8_WAIT_L(0); PG8_MMA(0, 1, At, B1); PG8_BAR;
;             PG8_LDA(At, 1, 1); PG8_STAGE(PG8_SA(1, 0), a3, voffA);
;             PG8_BAR; PG8_WAIT_L(0); PG8_MMA(1, 0, At, B0); PG8_BAR; PG8_SCHED;
;             PG8_STAGE(PG8_SB(1, 1), b3 + hstepB, voffB);
;             PG8_WAIT_V(6); PG8_BAR; PG8_MMA(1, 1, At, B1); PG8_BAR;
	s_waitcnt lgkmcnt(0)
	s_waitcnt lgkmcnt(0)
	v_mfma_f32_16x16x32_bf16 v[124:127], v[144:147], v[174:177], v[124:127]
	v_mfma_f32_16x16x32_bf16 v[128:131], v[166:169], v[174:177], v[128:131]
	v_mfma_f32_16x16x32_bf16 v[108:111], v[144:147], v[194:197], v[108:111]
	v_mfma_f32_16x16x32_bf16 v[112:115], v[166:169], v[194:197], v[112:115]
	v_mfma_f32_16x16x32_bf16 v[92:95], v[144:147], v[202:205], v[92:95]
	v_mfma_f32_16x16x32_bf16 v[96:99], v[166:169], v[202:205], v[96:99]
	v_mfma_f32_16x16x32_bf16 v[76:79], v[144:147], v[210:213], v[76:79]
	v_mfma_f32_16x16x32_bf16 v[80:83], v[166:169], v[210:213], v[80:83]
	v_mfma_f32_16x16x32_bf16 v[124:127], v[162:165], v[190:193], v[124:127]
	v_mfma_f32_16x16x32_bf16 v[128:131], v[170:173], v[190:193], v[128:131]
	v_mfma_f32_16x16x32_bf16 v[108:111], v[162:165], v[198:201], v[108:111]
	v_mfma_f32_16x16x32_bf16 v[112:115], v[170:173], v[198:201], v[112:115]
	v_mfma_f32_16x16x32_bf16 v[92:95], v[162:165], v[206:209], v[92:95]
	v_mfma_f32_16x16x32_bf16 v[96:99], v[170:173], v[206:209], v[96:99]
	v_mfma_f32_16x16x32_bf16 v[76:79], v[162:165], v[214:217], v[76:79]
	v_mfma_f32_16x16x32_bf16 v[80:83], v[170:173], v[214:217], v[80:83]
	s_barrier
	s_add_i32 s22, 0, 0x1c000
	s_add_i32 s23, s55, s38
	v_add_u32_e32 v157, s22, v140
	v_lshl_add_u64 v[178:179], v[178:179], 0, s[30:31]
	s_mov_b32 m0, s23
	ds_read_b128 v[218:221], v157
	ds_read_b128 v[222:225], v157 offset:1024
	ds_read_b128 v[226:229], v157 offset:2048
	ds_read_b128 v[230:233], v157 offset:3072
	global_load_lds_dwordx4 v[178:179], off
	v_lshl_add_u64 v[178:179], v[234:235], 0, s[30:31]
	s_add_i32 m0, s23, 0x2000
	s_nop 0
	global_load_lds_dwordx4 v[178:179], off
	s_barrier
	s_waitcnt lgkmcnt(0)
	s_waitcnt lgkmcnt(0)
	v_mfma_f32_16x16x32_bf16 v[116:119], v[218:221], v[174:177], v[116:119]
	v_mfma_f32_16x16x32_bf16 v[120:123], v[226:229], v[174:177], v[120:123]
	v_mfma_f32_16x16x32_bf16 v[100:103], v[218:221], v[194:197], v[100:103]
	v_mfma_f32_16x16x32_bf16 v[104:107], v[226:229], v[194:197], v[104:107]
	v_mfma_f32_16x16x32_bf16 v[84:87], v[218:221], v[202:205], v[84:87]
	v_mfma_f32_16x16x32_bf16 v[88:91], v[226:229], v[202:205], v[88:91]
	v_mfma_f32_16x16x32_bf16 v[68:71], v[218:221], v[210:213], v[68:71]
	v_mfma_f32_16x16x32_bf16 v[72:75], v[226:229], v[210:213], v[72:75]
	v_mfma_f32_16x16x32_bf16 v[116:119], v[222:225], v[190:193], v[116:119]
	v_mfma_f32_16x16x32_bf16 v[120:123], v[230:233], v[190:193], v[120:123]
	v_mfma_f32_16x16x32_bf16 v[100:103], v[222:225], v[198:201], v[100:103]
	v_mfma_f32_16x16x32_bf16 v[104:107], v[230:233], v[198:201], v[104:107]
	v_mfma_f32_16x16x32_bf16 v[84:87], v[222:225], v[206:209], v[84:87]
	v_mfma_f32_16x16x32_bf16 v[88:91], v[230:233], v[206:209], v[88:91]
	v_mfma_f32_16x16x32_bf16 v[68:71], v[222:225], v[214:217], v[68:71]
	v_mfma_f32_16x16x32_bf16 v[72:75], v[230:233], v[214:217], v[72:75]
	s_mov_b32 m0, s43
	v_lshl_add_u64 v[178:179], v[236:237], 0, s[30:31]
	s_barrier
	ds_read_b128 v[174:177], v143 offset:49152
	ds_read_b128 v[190:193], v143 offset:50176
	ds_read_b128 v[194:197], v143 offset:51200
	ds_read_b128 v[198:201], v143 offset:52224
	ds_read_b128 v[202:205], v143 offset:53248
	ds_read_b128 v[206:209], v143 offset:54272
	ds_read_b128 v[210:213], v143 offset:55296
	ds_read_b128 v[214:217], v143 offset:56320
	global_load_lds_dwordx4 v[178:179], off
	v_lshl_add_u64 v[178:179], v[238:239], 0, s[30:31]
	s_mov_b32 m0, s46
	s_nop 0
	global_load_lds_dwordx4 v[178:179], off
	s_barrier
	s_waitcnt lgkmcnt(0)
	s_waitcnt lgkmcnt(0)
	v_mfma_f32_16x16x32_bf16 v[60:63], v[144:147], v[174:177], v[60:63]
	v_mfma_f32_16x16x32_bf16 v[64:67], v[166:169], v[174:177], v[64:67]
	v_mfma_f32_16x16x32_bf16 v[44:47], v[144:147], v[194:197], v[44:47]
	v_mfma_f32_16x16x32_bf16 v[48:51], v[166:169], v[194:197], v[48:51]
	v_mfma_f32_16x16x32_bf16 v[28:31], v[144:147], v[202:205], v[28:31]
	v_mfma_f32_16x16x32_bf16 v[32:35], v[166:169], v[202:205], v[32:35]
	v_mfma_f32_16x16x32_bf16 v[12:15], v[144:147], v[210:213], v[12:15]
	v_mfma_f32_16x16x32_bf16 v[16:19], v[166:169], v[210:213], v[16:19]
	v_mfma_f32_16x16x32_bf16 v[60:63], v[162:165], v[190:193], v[60:63]
	v_mfma_f32_16x16x32_bf16 v[64:67], v[170:173], v[190:193], v[64:67]
	v_mfma_f32_16x16x32_bf16 v[44:47], v[162:165], v[198:201], v[44:47]
	v_mfma_f32_16x16x32_bf16 v[48:51], v[170:173], v[198:201], v[48:51]
	v_mfma_f32_16x16x32_bf16 v[28:31], v[162:165], v[206:209], v[28:31]
	v_mfma_f32_16x16x32_bf16 v[32:35], v[170:173], v[206:209], v[32:35]
	v_mfma_f32_16x16x32_bf16 v[12:15], v[162:165], v[214:217], v[12:15]
	v_mfma_f32_16x16x32_bf16 v[16:19], v[170:173], v[214:217], v[16:19]
	s_waitcnt vmcnt(4)
	s_barrier
	s_add_u32 s18, s18, 0x20080
	s_addc_u32 s19, s19, 0
	s_add_i32 s22, s22, s38
	s_mov_b32 m0, s22
	s_nop 0
	global_load_lds_dwordx4 v2, s[18:19]
	v_lshl_add_u64 v[144:145], s[18:19], 0, v[0:1]
	s_add_i32 m0, s22, 0x2000
	s_nop 0
	global_load_lds_dwordx4 v[144:145], off
	s_waitcnt vmcnt(6)
	s_barrier
	s_cmp_eq_u32 s54, 28
	s_cbranch_scc1 .Lproj_b0_skip
	v_add_u32_e32 v157, 0x10000, v140
	ds_read_b128 v[144:147], v157
	ds_read_b128 v[162:165], v157 offset:1024
	ds_read_b128 v[166:169], v157 offset:2048
	ds_read_b128 v[170:173], v157 offset:3072
; #define PG8_WAIT_V(n) asm volatile("s_waitcnt vmcnt(" #n ")" ::: "memory")
; #define PG8_BAR __builtin_amdgcn_s_barrier()
; template <class Epi>
; __device__ __forceinline__ void gemm_phase(LAS unsigned char* lds, const Gemm g, const StaticOrder& S, const Epi& E, const int tid) {
;     ...
;             PG8_WAIT_V(6); PG8_BAR; PG8_MMA(1, 1, At, B1); PG8_BAR;
;         }
;     __device__ __forceinline__ void operator()(f32x4 (&acc)[2][2][4][2], const pg8::Unit& u, int wr, int wc, int fr, int fq) const {
;         const bool hi = fr >= 8;
;         const int row0 = u.pm * 256 + wr * 64 + (fr & 7), col = u.pn * 256 + wc * 64 + fq * 8 + (hi ? 32 : 0);
; #pragma unroll
;         for (int ai = 0; ai < 2; ++ai)
; #pragma unroll
;             for (int m = 0; m < 4; ++m) {
;                 const h8 x0 = pack8(acc[ai][0][m][0], acc[ai][0][m][1]), x1 = pack8(acc[ai][1][m][0], acc[ai][1][m][1]);
;                 const i32x4 snd = hi ? __builtin_bit_cast(i32x4, x0) : __builtin_bit_cast(i32x4, x1);
;                 i32x4 rcv;
; #pragma unroll
;                 for (int d = 0; d < 4; ++d) rcv[d] = __builtin_amdgcn_update_dpp(0, snd[d], 0x128  , 0xF, 0xF, false);
;                 const h8 rv = __builtin_bit_cast(h8, rcv);
;                 const h8 vA = hi ? rv : x0;
;                 const h8 vB = hi ? x1 : rv;
;                 half_t* rowp = O + (size_t)(row0 + ai * 128 + m * 16) * NIN + col;
;                 __builtin_nontemporal_store(vA, (h8*)rowp); __builtin_nontemporal_store(vB, (h8*)(rowp + (size_t)8 * NIN)); }
.Lproj_b0_skip:
	v_mfma_f32_16x16x32_bf16 v[52:55], v[218:221], v[174:177], v[52:55]
	v_mfma_f32_16x16x32_bf16 v[56:59], v[226:229], v[174:177], v[56:59]
	v_mfma_f32_16x16x32_bf16 v[36:39], v[218:221], v[194:197], v[36:39]
	v_mfma_f32_16x16x32_bf16 v[40:43], v[226:229], v[194:197], v[40:43]
	v_mfma_f32_16x16x32_bf16 v[20:23], v[218:221], v[202:205], v[20:23]
	v_mfma_f32_16x16x32_bf16 v[24:27], v[226:229], v[202:205], v[24:27]
	v_mfma_f32_16x16x32_bf16 v[8:11], v[218:221], v[210:213], v[8:11]
	v_mfma_f32_16x16x32_bf16 v[4:7], v[226:229], v[210:213], v[4:7]
	v_mfma_f32_16x16x32_bf16 v[52:55], v[222:225], v[190:193], v[52:55]
	v_mfma_f32_16x16x32_bf16 v[56:59], v[230:233], v[190:193], v[56:59]
	v_mfma_f32_16x16x32_bf16 v[36:39], v[222:225], v[198:201], v[36:39]
	v_mfma_f32_16x16x32_bf16 v[40:43], v[230:233], v[198:201], v[40:43]
	v_mfma_f32_16x16x32_bf16 v[20:23], v[222:225], v[206:209], v[20:23]
	v_mfma_f32_16x16x32_bf16 v[24:27], v[230:233], v[206:209], v[24:27]
	v_mfma_f32_16x16x32_bf16 v[8:11], v[222:225], v[214:217], v[8:11]
	v_mfma_f32_16x16x32_bf16 v[4:7], v[230:233], v[214:217], v[4:7]
	s_add_i32 s54, s54, 2
	s_add_u32 s14, s14, 0x100
	s_addc_u32 s15, s15, 0
	s_add_u32 s52, s52, 0x100
	s_addc_u32 s53, s53, 0
	s_cmp_gt_u32 s54, 29
	s_barrier
	s_cbranch_scc0 .LBB0_332
	v_cvt_pk_f16_f32 v124, v124, v125
	v_cvt_pk_f16_f32 v116, v116, v117
	v_cvt_pk_f16_f32 v130, v130, v131
	v_cvt_pk_f16_f32 v131, v122, v123
	v_cvt_pk_f16_f32 v128, v128, v129
	v_cvt_pk_f16_f32 v129, v120, v121
	v_cvt_pk_f16_f32 v121, v126, v127
	v_cvt_pk_f16_f32 v118, v118, v119
	v_cndmask_b32_e64 v117, v116, v124, s[4:5]
	v_mov_b32_e32 v147, v3
	v_cndmask_b32_e64 v122, v131, v130, s[4:5]
	v_cndmask_b32_e64 v119, v118, v121, s[4:5]
	v_mov_b32_dpp v147, v117 row_ror:8 row_mask:0xf bank_mask:0xf
	v_mov_b32_e32 v117, v3
	v_mov_b32_e32 v125, v3
	v_lshl_or_b32 v144, s48, 8, v142
	v_cndmask_b32_e64 v120, v129, v128, s[4:5]
	v_mov_b32_dpp v117, v119 row_ror:8 row_mask:0xf bank_mask:0xf
	v_mov_b32_e32 v119, v3
	v_mov_b32_dpp v125, v122 row_ror:8 row_mask:0xf bank_mask:0xf
	v_lshl_add_u32 v146, s49, 8, v141
	v_ashrrev_i32_e32 v145, 31, v144
	v_mov_b32_dpp v119, v120 row_ror:8 row_mask:0xf bank_mask:0xf
	v_cndmask_b32_e64 v123, v130, v125, s[4:5]
	v_cndmask_b32_e64 v121, v121, v117, s[4:5]
	v_cndmask_b32_e64 v120, v124, v147, s[4:5]
	v_cndmask_b32_e64 v127, v125, v131, s[4:5]
	v_cndmask_b32_e64 v125, v117, v118, s[4:5]
	v_cndmask_b32_e64 v124, v147, v116, s[4:5]
	v_mov_b64_e32 v[116:117], s[36:37]
	v_cndmask_b32_e64 v122, v128, v119, s[4:5]
	v_cndmask_b32_e64 v126, v119, v129, s[4:5]
	v_mad_i64_i32 v[128:129], s[14:15], v146, s35, v[116:117]
	v_lshlrev_b64 v[118:119], 1, v[144:145]
	v_lshl_add_u64 v[128:129], v[128:129], 0, v[118:119]
	s_mov_b32 s1, 0x3c000
	global_store_dwordx4 v[128:129], v[120:123], off nt
	v_cvt_pk_f16_f32 v112, v112, v113
	v_cvt_pk_f16_f32 v104, v104, v105
	v_add_co_u32_e32 v120, vcc, s1, v128
	v_cvt_pk_f16_f32 v108, v108, v109
	s_nop 0
	v_addc_co_u32_e32 v121, vcc, 0, v129, vcc
	v_cvt_pk_f16_f32 v109, v100, v101
	global_store_dwordx4 v[120:121], v[124:127], off nt
	v_cvt_pk_f16_f32 v114, v114, v115
	v_cvt_pk_f16_f32 v106, v106, v107
	v_cndmask_b32_e64 v105, v104, v112, s[4:5]
	v_cndmask_b32_e64 v100, v109, v108, s[4:5]
	v_mov_b32_e32 v113, v3
	v_mov_b32_e32 v120, v3
	v_cndmask_b32_e64 v107, v106, v114, s[4:5]
	v_cvt_pk_f16_f32 v110, v110, v111
	v_cvt_pk_f16_f32 v111, v102, v103
	v_mov_b32_dpp v113, v100 row_ror:8 row_mask:0xf bank_mask:0xf
	v_mov_b32_dpp v120, v105 row_ror:8 row_mask:0xf bank_mask:0xf
	v_mov_b32_e32 v105, v3
	v_cndmask_b32_e64 v102, v111, v110, s[4:5]
	v_mov_b32_e32 v115, v3
	v_mov_b32_dpp v105, v107 row_ror:8 row_mask:0xf bank_mask:0xf
	v_cndmask_b32_e64 v100, v108, v113, s[4:5]
	v_or_b32_e32 v108, 16, v146
	v_mov_b32_dpp v115, v102 row_ror:8 row_mask:0xf bank_mask:0xf
	v_cndmask_b32_e64 v107, v105, v106, s[4:5]
	v_cndmask_b32_e64 v106, v120, v104, s[4:5]
	v_cndmask_b32_e64 v104, v113, v109, s[4:5]
	v_mad_i64_i32 v[108:109], s[14:15], v108, s35, v[116:117]
	v_cndmask_b32_e64 v103, v114, v105, s[4:5]
	v_cndmask_b32_e64 v102, v112, v120, s[4:5]
	v_cndmask_b32_e64 v101, v110, v115, s[4:5]
	v_lshl_add_u64 v[108:109], v[108:109], 0, v[118:119]
	global_store_dwordx4 v[108:109], v[100:103], off nt
	v_cndmask_b32_e64 v105, v115, v111, s[4:5]
	v_cvt_pk_f16_f32 v96, v96, v97
	v_add_co_u32_e32 v100, vcc, s1, v108
	v_cvt_pk_f16_f32 v88, v88, v89
	s_nop 0
	v_addc_co_u32_e32 v101, vcc, 0, v109, vcc
	v_cvt_pk_f16_f32 v92, v92, v93
	v_cvt_pk_f16_f32 v93, v84, v85
	global_store_dwordx4 v[100:101], v[104:107], off nt
	v_cvt_pk_f16_f32 v98, v98, v99
	v_cvt_pk_f16_f32 v90, v90, v91
	v_cndmask_b32_e64 v89, v88, v96, s[4:5]
	v_cndmask_b32_e64 v84, v93, v92, s[4:5]
	v_mov_b32_e32 v97, v3
	v_mov_b32_e32 v100, v3
	v_cndmask_b32_e64 v91, v90, v98, s[4:5]
	v_cvt_pk_f16_f32 v94, v94, v95
	v_cvt_pk_f16_f32 v95, v86, v87
	v_mov_b32_dpp v97, v84 row_ror:8 row_mask:0xf bank_mask:0xf
	v_mov_b32_dpp v100, v89 row_ror:8 row_mask:0xf bank_mask:0xf
	v_mov_b32_e32 v89, v3
	v_cndmask_b32_e64 v86, v95, v94, s[4:5]
	v_mov_b32_e32 v99, v3
	v_mov_b32_dpp v89, v91 row_ror:8 row_mask:0xf bank_mask:0xf
	v_cndmask_b32_e64 v84, v92, v97, s[4:5]
	v_or_b32_e32 v92, 32, v146
	v_mov_b32_dpp v99, v86 row_ror:8 row_mask:0xf bank_mask:0xf
	v_cndmask_b32_e64 v91, v89, v90, s[4:5]
	v_cndmask_b32_e64 v90, v100, v88, s[4:5]
	v_cndmask_b32_e64 v88, v97, v93, s[4:5]
	v_mad_i64_i32 v[92:93], s[14:15], v92, s35, v[116:117]
	v_cndmask_b32_e64 v87, v98, v89, s[4:5]
	v_cndmask_b32_e64 v86, v96, v100, s[4:5]
	v_cndmask_b32_e64 v85, v94, v99, s[4:5]
	v_lshl_add_u64 v[92:93], v[92:93], 0, v[118:119]
;     __device__ __forceinline__ void operator()(f32x4 (&acc)[2][2][4][2], const pg8::Unit& u, int wr, int wc, int fr, int fq) const {
;         const bool hi = fr >= 8;
;         const int row0 = u.pm * 256 + wr * 64 + (fr & 7), col = u.pn * 256 + wc * 64 + fq * 8 + (hi ? 32 : 0);
; #pragma unroll
;         for (int ai = 0; ai < 2; ++ai)
; #pragma unroll
;             for (int m = 0; m < 4; ++m) {
;                 const h8 x0 = pack8(acc[ai][0][m][0], acc[ai][0][m][1]), x1 = pack8(acc[ai][1][m][0], acc[ai][1][m][1]);
;                 const i32x4 snd = hi ? __builtin_bit_cast(i32x4, x0) : __builtin_bit_cast(i32x4, x1);
;                 i32x4 rcv;
; #pragma unroll
;                 for (int d = 0; d < 4; ++d) rcv[d] = __builtin_amdgcn_update_dpp(0, snd[d], 0x128  , 0xF, 0xF, false);
;                 const h8 rv = __builtin_bit_cast(h8, rcv);
;                 const h8 vA = hi ? rv : x0;
;                 const h8 vB = hi ? x1 : rv;
;                 half_t* rowp = O + (size_t)(row0 + ai * 128 + m * 16) * NIN + col;
;                 __builtin_nontemporal_store(vA, (h8*)rowp); __builtin_nontemporal_store(vB, (h8*)(rowp + (size_t)8 * NIN)); }
	global_store_dwordx4 v[92:93], v[84:87], off nt
	v_cndmask_b32_e64 v89, v99, v95, s[4:5]
	v_cvt_pk_f16_f32 v80, v80, v81
	v_add_co_u32_e32 v84, vcc, s1, v92
	v_cvt_pk_f16_f32 v72, v72, v73
	s_nop 0
	v_addc_co_u32_e32 v85, vcc, 0, v93, vcc
	v_cvt_pk_f16_f32 v76, v76, v77
	v_cvt_pk_f16_f32 v77, v68, v69
	global_store_dwordx4 v[84:85], v[88:91], off nt
	v_cvt_pk_f16_f32 v82, v82, v83
	v_cvt_pk_f16_f32 v74, v74, v75
	v_cndmask_b32_e64 v73, v72, v80, s[4:5]
	v_cndmask_b32_e64 v68, v77, v76, s[4:5]
	v_mov_b32_e32 v81, v3
	v_mov_b32_e32 v84, v3
	v_cndmask_b32_e64 v75, v74, v82, s[4:5]
	v_cvt_pk_f16_f32 v78, v78, v79
	v_cvt_pk_f16_f32 v79, v70, v71
	v_mov_b32_dpp v81, v68 row_ror:8 row_mask:0xf bank_mask:0xf
	v_mov_b32_dpp v84, v73 row_ror:8 row_mask:0xf bank_mask:0xf
	v_mov_b32_e32 v73, v3
	v_cndmask_b32_e64 v70, v79, v78, s[4:5]
	v_mov_b32_e32 v83, v3
	v_mov_b32_dpp v73, v75 row_ror:8 row_mask:0xf bank_mask:0xf
	v_cndmask_b32_e64 v68, v76, v81, s[4:5]
	v_or_b32_e32 v76, 48, v146
	v_mov_b32_dpp v83, v70 row_ror:8 row_mask:0xf bank_mask:0xf
	v_cndmask_b32_e64 v75, v73, v74, s[4:5]
	v_cndmask_b32_e64 v74, v84, v72, s[4:5]
	v_cndmask_b32_e64 v72, v81, v77, s[4:5]
	v_mad_i64_i32 v[76:77], s[14:15], v76, s35, v[116:117]
	v_cndmask_b32_e64 v71, v82, v73, s[4:5]
	v_cndmask_b32_e64 v70, v80, v84, s[4:5]
	v_cndmask_b32_e64 v69, v78, v83, s[4:5]
	v_lshl_add_u64 v[76:77], v[76:77], 0, v[118:119]
	global_store_dwordx4 v[76:77], v[68:71], off nt
	v_cndmask_b32_e64 v73, v83, v79, s[4:5]
	v_cvt_pk_f16_f32 v64, v64, v65
	v_add_co_u32_e32 v68, vcc, s1, v76
	v_cvt_pk_f16_f32 v56, v56, v57
	s_nop 0
	v_addc_co_u32_e32 v69, vcc, 0, v77, vcc
	global_store_dwordx4 v[68:69], v[72:75], off nt
	v_cvt_pk_f16_f32 v66, v66, v67
	v_cvt_pk_f16_f32 v58, v58, v59
	v_cndmask_b32_e64 v57, v56, v64, s[4:5]
	v_cvt_pk_f16_f32 v60, v60, v61
	v_cvt_pk_f16_f32 v61, v52, v53
	v_mov_b32_e32 v69, v3
	v_cndmask_b32_e64 v59, v58, v66, s[4:5]
	v_cvt_pk_f16_f32 v62, v62, v63
	v_cvt_pk_f16_f32 v63, v54, v55
	v_cndmask_b32_e64 v52, v61, v60, s[4:5]
	v_mov_b32_e32 v65, v3
	v_mov_b32_dpp v69, v57 row_ror:8 row_mask:0xf bank_mask:0xf
	v_mov_b32_e32 v57, v3
	v_add_u32_e32 v68, 0x80, v146
	v_cndmask_b32_e64 v54, v63, v62, s[4:5]
	v_mov_b32_dpp v65, v52 row_ror:8 row_mask:0xf bank_mask:0xf
	v_mov_b32_e32 v67, v3
	v_mov_b32_dpp v57, v59 row_ror:8 row_mask:0xf bank_mask:0xf
	v_cndmask_b32_e64 v52, v60, v65, s[4:5]
	v_mov_b32_dpp v67, v54 row_ror:8 row_mask:0xf bank_mask:0xf
	v_cndmask_b32_e64 v59, v57, v58, s[4:5]
	v_cndmask_b32_e64 v58, v69, v56, s[4:5]
	v_cndmask_b32_e64 v56, v65, v61, s[4:5]
	v_mad_i64_i32 v[60:61], s[14:15], v68, s35, v[116:117]
	v_cndmask_b32_e64 v55, v66, v57, s[4:5]
	v_cndmask_b32_e64 v54, v64, v69, s[4:5]
	v_cndmask_b32_e64 v53, v62, v67, s[4:5]
	v_lshl_add_u64 v[60:61], v[60:61], 0, v[118:119]
	global_store_dwordx4 v[60:61], v[52:55], off nt
	v_cndmask_b32_e64 v57, v67, v63, s[4:5]
	v_cvt_pk_f16_f32 v48, v48, v49
	v_add_co_u32_e32 v52, vcc, s1, v60
	v_cvt_pk_f16_f32 v40, v40, v41
	s_nop 0
	v_addc_co_u32_e32 v53, vcc, 0, v61, vcc
	v_cvt_pk_f16_f32 v44, v44, v45
	v_cvt_pk_f16_f32 v45, v36, v37
	global_store_dwordx4 v[52:53], v[56:59], off nt
	v_cvt_pk_f16_f32 v50, v50, v51
	v_cvt_pk_f16_f32 v42, v42, v43
	v_cndmask_b32_e64 v41, v40, v48, s[4:5]
	v_cndmask_b32_e64 v36, v45, v44, s[4:5]
	v_mov_b32_e32 v49, v3
	v_mov_b32_e32 v52, v3
	v_cndmask_b32_e64 v43, v42, v50, s[4:5]
	v_cvt_pk_f16_f32 v46, v46, v47
	v_cvt_pk_f16_f32 v47, v38, v39
	v_mov_b32_dpp v49, v36 row_ror:8 row_mask:0xf bank_mask:0xf
	v_mov_b32_dpp v52, v41 row_ror:8 row_mask:0xf bank_mask:0xf
	v_mov_b32_e32 v41, v3
	v_cndmask_b32_e64 v38, v47, v46, s[4:5]
	v_mov_b32_e32 v51, v3
	v_mov_b32_dpp v41, v43 row_ror:8 row_mask:0xf bank_mask:0xf
	v_cndmask_b32_e64 v36, v44, v49, s[4:5]
	v_add_u32_e32 v44, 0x90, v146
; #define PG8_WAIT_V(n) asm volatile("s_waitcnt vmcnt(" #n ")" ::: "memory")
; #define PG8_BAR __builtin_amdgcn_s_barrier()
; template <class Epi>
; __device__ __forceinline__ void gemm_phase(LAS unsigned char* lds, const Gemm g, const StaticOrder& S, const Epi& E, const int tid) {
;     ...
;     PG8_WAIT_V(0);
;     if (wr == 0) PG8_BAR;
;     PG8_BAR;
;     __device__ __forceinline__ void operator()(f32x4 (&acc)[2][2][4][2], const pg8::Unit& u, int wr, int wc, int fr, int fq) const {
;     ...
;                 const h8 x0 = pack8(acc[ai][0][m][0], acc[ai][0][m][1]), x1 = pack8(acc[ai][1][m][0], acc[ai][1][m][1]);
;                 const i32x4 snd = hi ? __builtin_bit_cast(i32x4, x0) : __builtin_bit_cast(i32x4, x1);
;                 i32x4 rcv;
; #pragma unroll
;                 for (int d = 0; d < 4; ++d) rcv[d] = __builtin_amdgcn_update_dpp(0, snd[d], 0x128  , 0xF, 0xF, false);
;                 const h8 rv = __builtin_bit_cast(h8, rcv);
;                 const h8 vA = hi ? rv : x0;
;                 const h8 vB = hi ? x1 : rv;
;                 half_t* rowp = O + (size_t)(row0 + ai * 128 + m * 16) * NIN + col;
;                 __builtin_nontemporal_store(vA, (h8*)rowp); __builtin_nontemporal_store(vB, (h8*)(rowp + (size_t)8 * NIN)); }
	v_mov_b32_dpp v51, v38 row_ror:8 row_mask:0xf bank_mask:0xf
	v_cndmask_b32_e64 v43, v41, v42, s[4:5]
	v_cndmask_b32_e64 v42, v52, v40, s[4:5]
	v_cndmask_b32_e64 v40, v49, v45, s[4:5]
	v_mad_i64_i32 v[44:45], s[14:15], v44, s35, v[116:117]
	v_cndmask_b32_e64 v39, v50, v41, s[4:5]
	v_cndmask_b32_e64 v38, v48, v52, s[4:5]
	v_cndmask_b32_e64 v37, v46, v51, s[4:5]
	v_lshl_add_u64 v[44:45], v[44:45], 0, v[118:119]
	global_store_dwordx4 v[44:45], v[36:39], off nt
	v_cndmask_b32_e64 v41, v51, v47, s[4:5]
	v_cvt_pk_f16_f32 v32, v32, v33
	v_add_co_u32_e32 v36, vcc, s1, v44
	v_cvt_pk_f16_f32 v24, v24, v25
	s_nop 0
	v_addc_co_u32_e32 v37, vcc, 0, v45, vcc
	v_cvt_pk_f16_f32 v28, v28, v29
	v_cvt_pk_f16_f32 v29, v20, v21
	global_store_dwordx4 v[36:37], v[40:43], off nt
	v_cvt_pk_f16_f32 v34, v34, v35
	v_cvt_pk_f16_f32 v26, v26, v27
	v_cndmask_b32_e64 v25, v24, v32, s[4:5]
	v_cndmask_b32_e64 v20, v29, v28, s[4:5]
	v_mov_b32_e32 v33, v3
	v_mov_b32_e32 v36, v3
	v_cndmask_b32_e64 v27, v26, v34, s[4:5]
	v_cvt_pk_f16_f32 v30, v30, v31
	v_cvt_pk_f16_f32 v31, v22, v23
	v_mov_b32_dpp v33, v20 row_ror:8 row_mask:0xf bank_mask:0xf
	v_mov_b32_dpp v36, v25 row_ror:8 row_mask:0xf bank_mask:0xf
	v_mov_b32_e32 v25, v3
	v_cvt_pk_f16_f32 v16, v16, v17
	v_cvt_pk_f16_f32 v17, v4, v5
	v_cvt_pk_f16_f32 v5, v14, v15
	v_cvt_pk_f16_f32 v14, v10, v11
	v_cvt_pk_f16_f32 v10, v12, v13
	v_cvt_pk_f16_f32 v8, v8, v9
	v_cndmask_b32_e64 v22, v31, v30, s[4:5]
	v_mov_b32_e32 v35, v3
	v_mov_b32_dpp v25, v27 row_ror:8 row_mask:0xf bank_mask:0xf
	v_cndmask_b32_e64 v20, v28, v33, s[4:5]
	v_add_u32_e32 v28, 0xa0, v146
	v_cndmask_b32_e64 v9, v8, v10, s[4:5]
	v_mov_b32_e32 v12, v3
	v_mov_b32_dpp v35, v22 row_ror:8 row_mask:0xf bank_mask:0xf
	v_cndmask_b32_e64 v27, v25, v26, s[4:5]
	v_cndmask_b32_e64 v26, v36, v24, s[4:5]
	v_cndmask_b32_e64 v24, v33, v29, s[4:5]
	v_mad_i64_i32 v[28:29], s[14:15], v28, s35, v[116:117]
	v_cvt_pk_f16_f32 v18, v18, v19
	v_cvt_pk_f16_f32 v19, v6, v7
	v_cndmask_b32_e64 v4, v17, v16, s[4:5]
	v_mov_b32_dpp v12, v9 row_ror:8 row_mask:0xf bank_mask:0xf
	v_mov_b32_e32 v13, v3
	v_cndmask_b32_e64 v23, v34, v25, s[4:5]
	v_cndmask_b32_e64 v22, v32, v36, s[4:5]
	v_cndmask_b32_e64 v21, v30, v35, s[4:5]
	v_lshl_add_u64 v[28:29], v[28:29], 0, v[118:119]
	v_cndmask_b32_e64 v6, v19, v18, s[4:5]
	v_cndmask_b32_e64 v7, v14, v5, s[4:5]
	v_mov_b32_e32 v9, v3
	v_mov_b32_dpp v13, v4 row_ror:8 row_mask:0xf bank_mask:0xf
	v_mov_b32_e32 v11, v3
	v_cndmask_b32_e64 v4, v10, v12, s[4:5]
	v_cndmask_b32_e64 v8, v12, v8, s[4:5]
	v_add_u32_e32 v12, 0xb0, v146
	global_store_dwordx4 v[28:29], v[20:23], off nt
	v_mov_b32_dpp v9, v7 row_ror:8 row_mask:0xf bank_mask:0xf
	v_mov_b32_dpp v11, v6 row_ror:8 row_mask:0xf bank_mask:0xf
	v_add_co_u32_e32 v20, vcc, s1, v28
	v_cndmask_b32_e64 v6, v16, v13, s[4:5]
	v_cndmask_b32_e64 v10, v13, v17, s[4:5]
	v_mad_i64_i32 v[12:13], s[14:15], v12, s35, v[116:117]
	v_addc_co_u32_e32 v21, vcc, 0, v29, vcc
	v_cndmask_b32_e64 v7, v18, v11, s[4:5]
	v_cndmask_b32_e64 v5, v5, v9, s[4:5]
	v_lshl_add_u64 v[12:13], v[12:13], 0, v[118:119]
	global_store_dwordx4 v[12:13], v[4:7], off nt
	v_cndmask_b32_e64 v25, v35, v31, s[4:5]
	v_cndmask_b32_e64 v11, v11, v19, s[4:5]
	v_add_co_u32_e32 v4, vcc, 0x3c000, v12
	v_cndmask_b32_e64 v9, v9, v14, s[4:5]
	s_nop 0
	v_addc_co_u32_e32 v5, vcc, 0, v13, vcc
	s_and_b64 vcc, exec, s[6:7]
	s_mov_b32 s48, s0
	s_mov_b32 s49, s8
	s_mov_b64 s[18:19], s[12:13]
	s_mov_b64 s[14:15], s[10:11]
	global_store_dwordx4 v[20:21], v[24:27], off nt
	global_store_dwordx4 v[4:5], v[8:11], off nt
	s_cbranch_vccz .LBB0_329
	s_waitcnt vmcnt(0)
	v_readlane_b32 s42, v251, 7
	v_readlane_b32 s46, v251, 9
	v_readlane_b32 s48, v251, 13
	s_cmpk_gt_u32 s20, 0xff
	v_readlane_b32 s43, v251, 8
	v_readlane_b32 s47, v251, 10
	v_readlane_b32 s49, v251, 14
	s_cbranch_scc1 .LBB0_336
	s_barrier
